# slab layout + local-mode barriers issue the L1 invalidate at barrier entry (overlapping the wait)
# baseline (speedup 1.0000x reference)
; __device__ __forceinline__ unsigned xb_ld(unsigned* p)              { return __hip_atomic_load(p, __ATOMIC_RELAXED, __HIP_MEMORY_SCOPE_AGENT); }
; __device__ __forceinline__ unsigned xb_add(unsigned* p, unsigned v) { return __hip_atomic_fetch_add(p, v, __ATOMIC_RELAXED, __HIP_MEMORY_SCOPE_AGENT); }
; #define XB_SPIN(cond, bar) do { unsigned _sp = 0; while (cond) { __builtin_amdgcn_s_sleep(1); \
;     if ((++_sp & 255u) == 0u) { if (xb_ld(&(bar)[XB_TMO])) break; if (_sp > XB_SPIN_CAP) { atomicAdd(&(bar)[XB_TMO], 1u); break; } } } } while (0)
; #define GRID_SYNC() do { xcd_barrier(xbar); } while (0)
; __device__ __forceinline__ void xcd_barrier(const XcdBarrier& b) {
;     asm volatile("s_waitcnt vmcnt(0)" ::: "memory");
;     __syncthreads();
;     if (threadIdx.x == 0) {
;         unsigned* bar = b.bar;
;         __builtin_amdgcn_s_waitcnt(0);
;         unsigned nloc = b.st[0], nx = b.st[1];
;         if (nloc == 0u) { xcd_barrier_complete(bar, b.x, nloc, nx); b.st[0] = nloc; b.st[1] = nx; }
;         const unsigned old = xb_add(&bar[XB_XSUB(b.x)], 1u);
;         const unsigned gen = old / nloc;
;         if (old + 1u == (gen + 1u) * nloc) {
;             __builtin_amdgcn_fence(__ATOMIC_RELEASE, "agent");
;             asm volatile("s_waitcnt vmcnt(0)" ::: "memory");
;             const unsigned og = xb_add(&bar[XB_TOP], 1u);
;             const unsigned tg = og / nx;
;             if (og + 1u == (tg + 1u) * nx) xb_add(&bar[XB_TOPGEN], 1u);
;             else XB_SPIN(xb_ld(&bar[XB_TOPGEN]) == tg, bar);
;             __builtin_amdgcn_fence(__ATOMIC_ACQUIRE, "agent");
;             xb_add(&bar[XB_XGEN(b.x)], 1u);
;             asm volatile("s_waitcnt vmcnt(0)" ::: "memory");
;         } else {
;             XB_SPIN(xb_ld(&bar[XB_XGEN(b.x)]) == gen, bar);
;             __builtin_amdgcn_fence(__ATOMIC_ACQUIRE, "agent");
;             asm volatile("s_waitcnt vmcnt(0)" ::: "memory");
;         }
;     }
;     __syncthreads();
; }
; __global__ void __launch_bounds__(512) fwd_megakernel(KArgs a) {
;     ...
;         if (layer < 3) GRID_SYNC();
.LBB0_163:
	s_or_b64 exec, exec, s[6:7]
	s_waitcnt vmcnt(0)
	s_branch .LBB0_164
.Lxb_local_5:
	v_mov_b32_e32 v0, 1
	v_readlane_b32 s4, v253, 40
	v_readlane_b32 s5, v253, 41
	s_nop 4
	global_atomic_add v181, v0, s[4:5]
	s_waitcnt vmcnt(0)

; __device__ __forceinline__ unsigned xb_add(unsigned* p, unsigned v) { return __hip_atomic_fetch_add(p, v, __ATOMIC_RELAXED, __HIP_MEMORY_SCOPE_AGENT); }
; __device__ __forceinline__ void xcd_barrier(const XcdBarrier& b) {
;     asm volatile("s_waitcnt vmcnt(0)" ::: "memory");
;     __syncthreads();
;     if (threadIdx.x == 0) {
;         unsigned* bar = b.bar;
;         __builtin_amdgcn_s_waitcnt(0);
;         unsigned nloc = b.st[0], nx = b.st[1];
;         if (nloc == 0u) { xcd_barrier_complete(bar, b.x, nloc, nx); b.st[0] = nloc; b.st[1] = nx; }
;         const unsigned old = xb_add(&bar[XB_XSUB(b.x)], 1u);
.LBB0_412:
	s_waitcnt vmcnt(0)
	s_waitcnt vmcnt(0)
	s_barrier
	s_and_saveexec_b64 s[0:1], s[96:97]
	v_readlane_b32 s64, v254, 51
	v_readlane_b32 s65, v254, 52
	s_cbranch_execz .LBB0_464
	v_readlane_b32 s4, v254, 33
	s_waitcnt vmcnt(0) expcnt(0) lgkmcnt(0)
	v_mov_b32_e32 v3, 0x20028
	ds_read_b32 v3, v3
	s_waitcnt lgkmcnt(0)
	v_cmp_eq_u32_e32 vcc, 0, v3
	s_cbranch_vccnz .Lxb_noearly_0
	buffer_inv sc1
.Lxb_noearly_0:
	s_nop 0
	v_mov_b32_e32 v0, s4
	ds_read_b32 v2, v0
	v_readlane_b32 s4, v254, 34
	s_waitcnt lgkmcnt(0)
	v_cmp_ne_u32_e32 vcc, 0, v2
	v_mov_b32_e32 v0, s4
	ds_read_b32 v0, v0
	s_cbranch_vccnz .LBB0_428
	s_mov_b32 s13, 1
	s_branch .LBB0_416

; __device__ __forceinline__ unsigned xb_ld(unsigned* p)              { return __hip_atomic_load(p, __ATOMIC_RELAXED, __HIP_MEMORY_SCOPE_AGENT); }
; __device__ __forceinline__ unsigned xb_add(unsigned* p, unsigned v) { return __hip_atomic_fetch_add(p, v, __ATOMIC_RELAXED, __HIP_MEMORY_SCOPE_AGENT); }
; #define XB_SPIN(cond, bar) do { unsigned _sp = 0; while (cond) { __builtin_amdgcn_s_sleep(1); \
;     if ((++_sp & 255u) == 0u) { if (xb_ld(&(bar)[XB_TMO])) break; if (_sp > XB_SPIN_CAP) { atomicAdd(&(bar)[XB_TMO], 1u); break; } } } } while (0)
; __device__ __forceinline__ void xcd_barrier(const XcdBarrier& b) {
;     ...
;         const unsigned old = xb_add(&bar[XB_XSUB(b.x)], 1u);
;         const unsigned gen = old / nloc;
;         if (old + 1u == (gen + 1u) * nloc) {
;             __builtin_amdgcn_fence(__ATOMIC_RELEASE, "agent");
;             asm volatile("s_waitcnt vmcnt(0)" ::: "memory");
;             const unsigned og = xb_add(&bar[XB_TOP], 1u);
;             const unsigned tg = og / nx;
;             if (og + 1u == (tg + 1u) * nx) xb_add(&bar[XB_TOPGEN], 1u);
;             else XB_SPIN(xb_ld(&bar[XB_TOPGEN]) == tg, bar);
;             __builtin_amdgcn_fence(__ATOMIC_ACQUIRE, "agent");
;             xb_add(&bar[XB_XGEN(b.x)], 1u);
;             asm volatile("s_waitcnt vmcnt(0)" ::: "memory");
;         } else {
;             XB_SPIN(xb_ld(&bar[XB_XGEN(b.x)]) == gen, bar);
;             __builtin_amdgcn_fence(__ATOMIC_ACQUIRE, "agent");
;             asm volatile("s_waitcnt vmcnt(0)" ::: "memory");
;         }
.LBB0_443:
	s_or_b64 exec, exec, s[6:7]
	s_waitcnt vmcnt(0)
	v_mov_b32_e32 v2, 0x20028
	ds_read_b32 v2, v2
	s_waitcnt lgkmcnt(0)
	v_cmp_ne_u32_e32 vcc, 0, v2
	s_cbranch_vccnz .Lxb_skipinv_0
	buffer_inv sc1
.Lxb_skipinv_0:
	s_waitcnt vmcnt(0)
.LBB0_444:
	s_andn2_saveexec_b64 s[4:5], s[4:5]
	s_cbranch_execz .LBB0_464
	s_mov_b64 s[4:5], exec
	v_mov_b32_e32 v1, 0x20028
	ds_read_b32 v1, v1
	s_waitcnt lgkmcnt(0)
	v_cmp_ne_u32_e32 vcc, 0, v1
	s_cbranch_vccnz .Lxb_local_0
	buffer_wbl2 sc1
	s_waitcnt lgkmcnt(0)
	s_waitcnt vmcnt(0)
	v_mbcnt_lo_u32_b32 v1, s4, 0
	v_mbcnt_hi_u32_b32 v1, s5, v1
	v_cmp_eq_u32_e32 vcc, 0, v1
	s_and_saveexec_b64 s[6:7], vcc
	s_cbranch_execz .LBB0_447
	s_bcnt1_i32_b64 s4, s[4:5]
	v_mov_b32_e32 v2, s4
	v_readlane_b32 s4, v253, 42
	v_readlane_b32 s5, v253, 43
	s_nop 4
	global_atomic_add v2, v181, v2, s[4:5] sc0

; __device__ __forceinline__ unsigned xb_add(unsigned* p, unsigned v) { return __hip_atomic_fetch_add(p, v, __ATOMIC_RELAXED, __HIP_MEMORY_SCOPE_AGENT); }
; __device__ __forceinline__ void xcd_barrier(const XcdBarrier& b) {
;     asm volatile("s_waitcnt vmcnt(0)" ::: "memory");
;     __syncthreads();
;     if (threadIdx.x == 0) {
;         unsigned* bar = b.bar;
;         __builtin_amdgcn_s_waitcnt(0);
;         unsigned nloc = b.st[0], nx = b.st[1];
;         if (nloc == 0u) { xcd_barrier_complete(bar, b.x, nloc, nx); b.st[0] = nloc; b.st[1] = nx; }
;         const unsigned old = xb_add(&bar[XB_XSUB(b.x)], 1u);
.LBB0_698:
	s_waitcnt vmcnt(0)
	s_waitcnt vmcnt(0) lgkmcnt(0)
	s_barrier
	s_and_saveexec_b64 s[0:1], s[96:97]
	v_readlane_b32 s80, v254, 43
	v_readlane_b32 s81, v254, 44
	v_readlane_b32 s61, v254, 31
	s_mov_b32 s35, 0xf800000
	s_cbranch_execz .LBB0_750
	v_readlane_b32 s4, v254, 33
	s_waitcnt vmcnt(0) expcnt(0) lgkmcnt(0)
	v_mov_b32_e32 v3, 0x20028
	ds_read_b32 v3, v3
	s_waitcnt lgkmcnt(0)
	v_cmp_eq_u32_e32 vcc, 0, v3
	s_cbranch_vccnz .Lxb_noearly_1
	buffer_inv sc1

; __device__ __forceinline__ unsigned xb_ld(unsigned* p)              { return __hip_atomic_load(p, __ATOMIC_RELAXED, __HIP_MEMORY_SCOPE_AGENT); }
; __device__ __forceinline__ unsigned xb_add(unsigned* p, unsigned v) { return __hip_atomic_fetch_add(p, v, __ATOMIC_RELAXED, __HIP_MEMORY_SCOPE_AGENT); }
; #define XB_SPIN(cond, bar) do { unsigned _sp = 0; while (cond) { __builtin_amdgcn_s_sleep(1); \
;     if ((++_sp & 255u) == 0u) { if (xb_ld(&(bar)[XB_TMO])) break; if (_sp > XB_SPIN_CAP) { atomicAdd(&(bar)[XB_TMO], 1u); break; } } } } while (0)
; __device__ __forceinline__ void xcd_barrier(const XcdBarrier& b) {
;     ...
;         const unsigned old = xb_add(&bar[XB_XSUB(b.x)], 1u);
;         const unsigned gen = old / nloc;
;         if (old + 1u == (gen + 1u) * nloc) {
;             __builtin_amdgcn_fence(__ATOMIC_RELEASE, "agent");
;             asm volatile("s_waitcnt vmcnt(0)" ::: "memory");
;             const unsigned og = xb_add(&bar[XB_TOP], 1u);
;             const unsigned tg = og / nx;
;             if (og + 1u == (tg + 1u) * nx) xb_add(&bar[XB_TOPGEN], 1u);
;             else XB_SPIN(xb_ld(&bar[XB_TOPGEN]) == tg, bar);
.Lxb_skipinv_1:
	s_waitcnt vmcnt(0)
.LBB0_730:
	s_andn2_saveexec_b64 s[4:5], s[4:5]
	s_cbranch_execz .LBB0_750
	s_mov_b64 s[4:5], exec
	v_mov_b32_e32 v1, 0x20028
	ds_read_b32 v1, v1
	s_waitcnt lgkmcnt(0)
	v_cmp_ne_u32_e32 vcc, 0, v1
	s_cbranch_vccnz .Lxb_local_1
	buffer_wbl2 sc1
	s_waitcnt lgkmcnt(0)
	s_waitcnt vmcnt(0)
	v_mbcnt_lo_u32_b32 v1, s4, 0
	v_mbcnt_hi_u32_b32 v1, s5, v1
	v_cmp_eq_u32_e32 vcc, 0, v1
	s_and_saveexec_b64 s[6:7], vcc
	s_cbranch_execz .LBB0_733
	s_bcnt1_i32_b64 s4, s[4:5]
	v_mov_b32_e32 v2, s4
	v_readlane_b32 s4, v253, 42
	v_readlane_b32 s5, v253, 43
	s_nop 4
	global_atomic_add v2, v181, v2, s[4:5] sc0

; __device__ __forceinline__ unsigned xb_add(unsigned* p, unsigned v) { return __hip_atomic_fetch_add(p, v, __ATOMIC_RELAXED, __HIP_MEMORY_SCOPE_AGENT); }
; __device__ __forceinline__ void xcd_barrier(const XcdBarrier& b) {
;     asm volatile("s_waitcnt vmcnt(0)" ::: "memory");
;     __syncthreads();
;     if (threadIdx.x == 0) {
;         unsigned* bar = b.bar;
;         __builtin_amdgcn_s_waitcnt(0);
;         unsigned nloc = b.st[0], nx = b.st[1];
;         if (nloc == 0u) { xcd_barrier_complete(bar, b.x, nloc, nx); b.st[0] = nloc; b.st[1] = nx; }
;         const unsigned old = xb_add(&bar[XB_XSUB(b.x)], 1u);
.LBB0_821:
	s_waitcnt vmcnt(0)
	s_barrier
	s_and_saveexec_b64 s[4:5], s[96:97]
	s_cbranch_execz .LBB0_873
	v_readlane_b32 s6, v254, 33
	s_waitcnt vmcnt(0) expcnt(0) lgkmcnt(0)
	v_mov_b32_e32 v3, 0x20028
	ds_read_b32 v3, v3
	s_waitcnt lgkmcnt(0)
	v_cmp_eq_u32_e32 vcc, 0, v3
	s_cbranch_vccnz .Lxb_noearly_2
	buffer_inv sc1
.Lxb_noearly_2:
	s_nop 0
	v_mov_b32_e32 v0, s6
	ds_read_b32 v2, v0
	v_readlane_b32 s6, v254, 34
	s_waitcnt lgkmcnt(0)
	v_cmp_ne_u32_e32 vcc, 0, v2
	v_mov_b32_e32 v0, s6
	ds_read_b32 v0, v0
	s_cbranch_vccnz .LBB0_837
	s_mov_b32 s13, 1
	s_branch .LBB0_825

; __device__ __forceinline__ unsigned xb_ld(unsigned* p)              { return __hip_atomic_load(p, __ATOMIC_RELAXED, __HIP_MEMORY_SCOPE_AGENT); }
; __device__ __forceinline__ unsigned xb_add(unsigned* p, unsigned v) { return __hip_atomic_fetch_add(p, v, __ATOMIC_RELAXED, __HIP_MEMORY_SCOPE_AGENT); }
; #define XB_SPIN(cond, bar) do { unsigned _sp = 0; while (cond) { __builtin_amdgcn_s_sleep(1); \
;     if ((++_sp & 255u) == 0u) { if (xb_ld(&(bar)[XB_TMO])) break; if (_sp > XB_SPIN_CAP) { atomicAdd(&(bar)[XB_TMO], 1u); break; } } } } while (0)
; __device__ __forceinline__ void xcd_barrier(const XcdBarrier& b) {
;     ...
;         const unsigned old = xb_add(&bar[XB_XSUB(b.x)], 1u);
;         const unsigned gen = old / nloc;
;         if (old + 1u == (gen + 1u) * nloc) {
;             __builtin_amdgcn_fence(__ATOMIC_RELEASE, "agent");
;             asm volatile("s_waitcnt vmcnt(0)" ::: "memory");
;             const unsigned og = xb_add(&bar[XB_TOP], 1u);
;             const unsigned tg = og / nx;
;             if (og + 1u == (tg + 1u) * nx) xb_add(&bar[XB_TOPGEN], 1u);
;             else XB_SPIN(xb_ld(&bar[XB_TOPGEN]) == tg, bar);
;             __builtin_amdgcn_fence(__ATOMIC_ACQUIRE, "agent");
;             xb_add(&bar[XB_XGEN(b.x)], 1u);
;             asm volatile("s_waitcnt vmcnt(0)" ::: "memory");
;         } else {
;             XB_SPIN(xb_ld(&bar[XB_XGEN(b.x)]) == gen, bar);
;             __builtin_amdgcn_fence(__ATOMIC_ACQUIRE, "agent");
;             asm volatile("s_waitcnt vmcnt(0)" ::: "memory");
;         }
.LBB0_852:
	s_or_b64 exec, exec, s[28:29]
	s_waitcnt vmcnt(0)
	v_mov_b32_e32 v2, 0x20028
	ds_read_b32 v2, v2
	s_waitcnt lgkmcnt(0)
	v_cmp_ne_u32_e32 vcc, 0, v2
	s_cbranch_vccnz .Lxb_skipinv_2
	buffer_inv sc1
.Lxb_skipinv_2:
	s_waitcnt vmcnt(0)
.LBB0_853:
	s_andn2_saveexec_b64 s[6:7], s[6:7]
	s_cbranch_execz .LBB0_873
	s_mov_b64 s[6:7], exec
	v_mov_b32_e32 v1, 0x20028
	ds_read_b32 v1, v1
	s_waitcnt lgkmcnt(0)
	v_cmp_ne_u32_e32 vcc, 0, v1
	s_cbranch_vccnz .Lxb_local_2
	buffer_wbl2 sc1
	s_waitcnt lgkmcnt(0)
	s_waitcnt vmcnt(0)
	v_mbcnt_lo_u32_b32 v1, s6, 0
	v_mbcnt_hi_u32_b32 v1, s7, v1
	v_cmp_eq_u32_e32 vcc, 0, v1
	s_and_saveexec_b64 s[28:29], vcc
	s_cbranch_execz .LBB0_856
	s_bcnt1_i32_b64 s6, s[6:7]
	v_mov_b32_e32 v2, s6
	v_readlane_b32 s6, v253, 42
	v_readlane_b32 s7, v253, 43
	s_nop 4
	global_atomic_add v2, v181, v2, s[6:7] sc0

; __device__ __forceinline__ unsigned xb_ld(unsigned* p)              { return __hip_atomic_load(p, __ATOMIC_RELAXED, __HIP_MEMORY_SCOPE_AGENT); }
; __device__ __forceinline__ unsigned xb_add(unsigned* p, unsigned v) { return __hip_atomic_fetch_add(p, v, __ATOMIC_RELAXED, __HIP_MEMORY_SCOPE_AGENT); }
; #define XB_SPIN(cond, bar) do { unsigned _sp = 0; while (cond) { __builtin_amdgcn_s_sleep(1); \
;     if ((++_sp & 255u) == 0u) { if (xb_ld(&(bar)[XB_TMO])) break; if (_sp > XB_SPIN_CAP) { atomicAdd(&(bar)[XB_TMO], 1u); break; } } } } while (0)
; __device__ __forceinline__ void xcd_barrier(const XcdBarrier& b) {
;     ...
;         const unsigned old = xb_add(&bar[XB_XSUB(b.x)], 1u);
;         const unsigned gen = old / nloc;
;         if (old + 1u == (gen + 1u) * nloc) {
;             __builtin_amdgcn_fence(__ATOMIC_RELEASE, "agent");
;             asm volatile("s_waitcnt vmcnt(0)" ::: "memory");
;             const unsigned og = xb_add(&bar[XB_TOP], 1u);
;             const unsigned tg = og / nx;
;             if (og + 1u == (tg + 1u) * nx) xb_add(&bar[XB_TOPGEN], 1u);
;             else XB_SPIN(xb_ld(&bar[XB_TOPGEN]) == tg, bar);
;             __builtin_amdgcn_fence(__ATOMIC_ACQUIRE, "agent");
;             xb_add(&bar[XB_XGEN(b.x)], 1u);
;             asm volatile("s_waitcnt vmcnt(0)" ::: "memory");
;         } else {
;             XB_SPIN(xb_ld(&bar[XB_XGEN(b.x)]) == gen, bar);
;             __builtin_amdgcn_fence(__ATOMIC_ACQUIRE, "agent");
;             asm volatile("s_waitcnt vmcnt(0)" ::: "memory");
;         }
.LBB0_872:
	s_or_b64 exec, exec, s[28:29]
	s_waitcnt vmcnt(0)
	s_branch .LBB0_873
.Lxb_local_2:
	v_mov_b32_e32 v0, 1
	v_readlane_b32 s6, v253, 40
	v_readlane_b32 s7, v253, 41
	s_nop 4
	global_atomic_add v181, v0, s[6:7]
	s_waitcnt vmcnt(0)

; __device__ __forceinline__ unsigned xb_add(unsigned* p, unsigned v) { return __hip_atomic_fetch_add(p, v, __ATOMIC_RELAXED, __HIP_MEMORY_SCOPE_AGENT); }
; __device__ __forceinline__ void xcd_barrier(const XcdBarrier& b) {
;     asm volatile("s_waitcnt vmcnt(0)" ::: "memory");
;     __syncthreads();
;     if (threadIdx.x == 0) {
;         unsigned* bar = b.bar;
;         __builtin_amdgcn_s_waitcnt(0);
;         unsigned nloc = b.st[0], nx = b.st[1];
;         if (nloc == 0u) { xcd_barrier_complete(bar, b.x, nloc, nx); b.st[0] = nloc; b.st[1] = nx; }
;         const unsigned old = xb_add(&bar[XB_XSUB(b.x)], 1u);
.LBB0_998:
	s_waitcnt vmcnt(0)
	s_waitcnt lgkmcnt(0)
	s_barrier
	s_and_saveexec_b64 s[0:1], s[96:97]
	s_cbranch_execz .LBB0_1050
	v_readlane_b32 s4, v254, 33
	s_waitcnt vmcnt(0) expcnt(0) lgkmcnt(0)
	v_mov_b32_e32 v3, 0x20028
	ds_read_b32 v3, v3
	s_waitcnt lgkmcnt(0)
	v_cmp_eq_u32_e32 vcc, 0, v3
	s_cbranch_vccnz .Lxb_noearly_3
	buffer_inv sc1

; __device__ __forceinline__ unsigned xb_ld(unsigned* p)              { return __hip_atomic_load(p, __ATOMIC_RELAXED, __HIP_MEMORY_SCOPE_AGENT); }
; __device__ __forceinline__ unsigned xb_add(unsigned* p, unsigned v) { return __hip_atomic_fetch_add(p, v, __ATOMIC_RELAXED, __HIP_MEMORY_SCOPE_AGENT); }
; #define XB_SPIN(cond, bar) do { unsigned _sp = 0; while (cond) { __builtin_amdgcn_s_sleep(1); \
;     if ((++_sp & 255u) == 0u) { if (xb_ld(&(bar)[XB_TMO])) break; if (_sp > XB_SPIN_CAP) { atomicAdd(&(bar)[XB_TMO], 1u); break; } } } } while (0)
; __device__ __forceinline__ void xcd_barrier(const XcdBarrier& b) {
;     ...
;         const unsigned old = xb_add(&bar[XB_XSUB(b.x)], 1u);
;         const unsigned gen = old / nloc;
;         if (old + 1u == (gen + 1u) * nloc) {
;             __builtin_amdgcn_fence(__ATOMIC_RELEASE, "agent");
;             asm volatile("s_waitcnt vmcnt(0)" ::: "memory");
;             const unsigned og = xb_add(&bar[XB_TOP], 1u);
;             const unsigned tg = og / nx;
;             if (og + 1u == (tg + 1u) * nx) xb_add(&bar[XB_TOPGEN], 1u);
;             else XB_SPIN(xb_ld(&bar[XB_TOPGEN]) == tg, bar);
.Lxb_skipinv_3:
	s_waitcnt vmcnt(0)
.LBB0_1030:
	s_andn2_saveexec_b64 s[4:5], s[4:5]
	s_cbranch_execz .LBB0_1050
	s_mov_b64 s[4:5], exec
	v_mov_b32_e32 v1, 0x20028
	ds_read_b32 v1, v1
	s_waitcnt lgkmcnt(0)
	v_cmp_ne_u32_e32 vcc, 0, v1
	s_cbranch_vccnz .Lxb_local_3
	buffer_wbl2 sc1
	s_waitcnt lgkmcnt(0)
	s_waitcnt vmcnt(0)
	v_mbcnt_lo_u32_b32 v1, s4, 0
	v_mbcnt_hi_u32_b32 v1, s5, v1
	v_cmp_eq_u32_e32 vcc, 0, v1
	s_and_saveexec_b64 s[6:7], vcc
	s_cbranch_execz .LBB0_1033
	s_bcnt1_i32_b64 s4, s[4:5]
	v_mov_b32_e32 v2, s4
	v_readlane_b32 s4, v253, 42
	v_readlane_b32 s5, v253, 43
	s_nop 4
	global_atomic_add v2, v181, v2, s[4:5] sc0

; __device__ __forceinline__ unsigned xb_add(unsigned* p, unsigned v) { return __hip_atomic_fetch_add(p, v, __ATOMIC_RELAXED, __HIP_MEMORY_SCOPE_AGENT); }
; __device__ __forceinline__ void xcd_barrier(const XcdBarrier& b) {
;     asm volatile("s_waitcnt vmcnt(0)" ::: "memory");
;     __syncthreads();
;     if (threadIdx.x == 0) {
;         unsigned* bar = b.bar;
;         __builtin_amdgcn_s_waitcnt(0);
;         unsigned nloc = b.st[0], nx = b.st[1];
;         if (nloc == 0u) { xcd_barrier_complete(bar, b.x, nloc, nx); b.st[0] = nloc; b.st[1] = nx; }
;         const unsigned old = xb_add(&bar[XB_XSUB(b.x)], 1u);
.LBB0_1074:
	s_waitcnt vmcnt(0)
	s_waitcnt vmcnt(0)
	s_barrier
	s_and_saveexec_b64 s[0:1], s[96:97]
	s_cbranch_execz .LBB0_875
	v_readlane_b32 s4, v254, 33
	s_waitcnt vmcnt(0) expcnt(0) lgkmcnt(0)
	v_mov_b32_e32 v3, 0x20028
	ds_read_b32 v3, v3
	s_waitcnt lgkmcnt(0)
	v_cmp_eq_u32_e32 vcc, 0, v3
	s_cbranch_vccnz .Lxb_noearly_4
	buffer_inv sc1

; __device__ __forceinline__ unsigned xb_ld(unsigned* p)              { return __hip_atomic_load(p, __ATOMIC_RELAXED, __HIP_MEMORY_SCOPE_AGENT); }
; __device__ __forceinline__ unsigned xb_add(unsigned* p, unsigned v) { return __hip_atomic_fetch_add(p, v, __ATOMIC_RELAXED, __HIP_MEMORY_SCOPE_AGENT); }
; #define XB_SPIN(cond, bar) do { unsigned _sp = 0; while (cond) { __builtin_amdgcn_s_sleep(1); \
;     if ((++_sp & 255u) == 0u) { if (xb_ld(&(bar)[XB_TMO])) break; if (_sp > XB_SPIN_CAP) { atomicAdd(&(bar)[XB_TMO], 1u); break; } } } } while (0)
; __device__ __forceinline__ void xcd_barrier(const XcdBarrier& b) {
;     ...
;         const unsigned old = xb_add(&bar[XB_XSUB(b.x)], 1u);
;         const unsigned gen = old / nloc;
;         if (old + 1u == (gen + 1u) * nloc) {
;             __builtin_amdgcn_fence(__ATOMIC_RELEASE, "agent");
;             asm volatile("s_waitcnt vmcnt(0)" ::: "memory");
;             const unsigned og = xb_add(&bar[XB_TOP], 1u);
;             const unsigned tg = og / nx;
;             if (og + 1u == (tg + 1u) * nx) xb_add(&bar[XB_TOPGEN], 1u);
;             else XB_SPIN(xb_ld(&bar[XB_TOPGEN]) == tg, bar);
.Lxb_skipinv_4:
	s_waitcnt vmcnt(0)
.LBB0_1106:
	s_andn2_saveexec_b64 s[4:5], s[4:5]
	s_cbranch_execz .LBB0_875
	s_mov_b64 s[4:5], exec
	v_mov_b32_e32 v1, 0x20028
	ds_read_b32 v1, v1
	s_waitcnt lgkmcnt(0)
	v_cmp_ne_u32_e32 vcc, 0, v1
	s_cbranch_vccnz .Lxb_local_4
	buffer_wbl2 sc1
	s_waitcnt lgkmcnt(0)
	s_waitcnt vmcnt(0)
	v_mbcnt_lo_u32_b32 v1, s4, 0
	v_mbcnt_hi_u32_b32 v1, s5, v1
	v_cmp_eq_u32_e32 vcc, 0, v1
	s_and_saveexec_b64 s[6:7], vcc
	s_cbranch_execz .LBB0_1109
	s_bcnt1_i32_b64 s4, s[4:5]
	v_mov_b32_e32 v2, s4
	v_readlane_b32 s4, v253, 42
	v_readlane_b32 s5, v253, 43
	s_nop 4
	global_atomic_add v2, v181, v2, s[4:5] sc0

; __device__ __forceinline__ unsigned xb_add(unsigned* p, unsigned v) { return __hip_atomic_fetch_add(p, v, __ATOMIC_RELAXED, __HIP_MEMORY_SCOPE_AGENT); }
; #define GRID_SYNC() do { xcd_barrier(xbar); } while (0)
; __device__ __forceinline__ void xcd_barrier(const XcdBarrier& b) {
;     asm volatile("s_waitcnt vmcnt(0)" ::: "memory");
;     __syncthreads();
;     if (threadIdx.x == 0) {
;         unsigned* bar = b.bar;
;         __builtin_amdgcn_s_waitcnt(0);
;         unsigned nloc = b.st[0], nx = b.st[1];
;         if (nloc == 0u) { xcd_barrier_complete(bar, b.x, nloc, nx); b.st[0] = nloc; b.st[1] = nx; }
;         const unsigned old = xb_add(&bar[XB_XSUB(b.x)], 1u);
; __global__ void __launch_bounds__(512) fwd_megakernel(KArgs a) {
;     ...
;         if (layer < 3) GRID_SYNC();
.LBB0_1125:
	v_readlane_b32 s0, v255, 11
	v_readlane_b32 s1, v255, 12
	s_and_b64 vcc, exec, s[0:1]
	s_cbranch_vccz .LBB0_165
	s_waitcnt vmcnt(0)
	s_waitcnt lgkmcnt(0)
	s_barrier
	s_and_saveexec_b64 s[0:1], s[96:97]
	s_cbranch_execz .LBB0_164
	v_readlane_b32 s4, v254, 33
	s_waitcnt vmcnt(0) expcnt(0) lgkmcnt(0)
	v_mov_b32_e32 v3, 0x20028
	ds_read_b32 v3, v3
	s_waitcnt lgkmcnt(0)
	v_cmp_eq_u32_e32 vcc, 0, v3
	s_cbranch_vccnz .Lxb_noearly_5
	buffer_inv sc1

; __device__ __forceinline__ unsigned xb_ld(unsigned* p)              { return __hip_atomic_load(p, __ATOMIC_RELAXED, __HIP_MEMORY_SCOPE_AGENT); }
; __device__ __forceinline__ unsigned xb_add(unsigned* p, unsigned v) { return __hip_atomic_fetch_add(p, v, __ATOMIC_RELAXED, __HIP_MEMORY_SCOPE_AGENT); }
; #define XB_SPIN(cond, bar) do { unsigned _sp = 0; while (cond) { __builtin_amdgcn_s_sleep(1); \
;     if ((++_sp & 255u) == 0u) { if (xb_ld(&(bar)[XB_TMO])) break; if (_sp > XB_SPIN_CAP) { atomicAdd(&(bar)[XB_TMO], 1u); break; } } } } while (0)
; __device__ __forceinline__ void xcd_barrier(const XcdBarrier& b) {
;     ...
;         const unsigned old = xb_add(&bar[XB_XSUB(b.x)], 1u);
;         const unsigned gen = old / nloc;
;         if (old + 1u == (gen + 1u) * nloc) {
;             __builtin_amdgcn_fence(__ATOMIC_RELEASE, "agent");
;             asm volatile("s_waitcnt vmcnt(0)" ::: "memory");
;             const unsigned og = xb_add(&bar[XB_TOP], 1u);
;             const unsigned tg = og / nx;
;             if (og + 1u == (tg + 1u) * nx) xb_add(&bar[XB_TOPGEN], 1u);
;             else XB_SPIN(xb_ld(&bar[XB_TOPGEN]) == tg, bar);
;             __builtin_amdgcn_fence(__ATOMIC_ACQUIRE, "agent");
;             xb_add(&bar[XB_XGEN(b.x)], 1u);
;             asm volatile("s_waitcnt vmcnt(0)" ::: "memory");
;         } else {
;             XB_SPIN(xb_ld(&bar[XB_XGEN(b.x)]) == gen, bar);
;             __builtin_amdgcn_fence(__ATOMIC_ACQUIRE, "agent");
;             asm volatile("s_waitcnt vmcnt(0)" ::: "memory");
;         }
.Lxb_skipinv_5:
	s_waitcnt vmcnt(0)
.LBB0_1158:
	s_andn2_saveexec_b64 s[4:5], s[4:5]
	s_cbranch_execz .LBB0_164
	s_mov_b64 s[4:5], exec
	v_mov_b32_e32 v1, 0x20028
	ds_read_b32 v1, v1
	s_waitcnt lgkmcnt(0)
	v_cmp_ne_u32_e32 vcc, 0, v1
	s_cbranch_vccnz .Lxb_local_5
	buffer_wbl2 sc1
	s_waitcnt lgkmcnt(0)
	s_waitcnt vmcnt(0)
	v_mbcnt_lo_u32_b32 v1, s4, 0
	v_mbcnt_hi_u32_b32 v1, s5, v1
	v_cmp_eq_u32_e32 vcc, 0, v1
	s_and_saveexec_b64 s[6:7], vcc
	s_cbranch_execz .LBB0_1161
	s_bcnt1_i32_b64 s4, s[4:5]
	v_mov_b32_e32 v2, s4
	v_readlane_b32 s4, v253, 42
	v_readlane_b32 s5, v253, 43
	s_nop 4
	global_atomic_add v2, v181, v2, s[4:5] sc0
